# HGRN phase C: also batch the LDS reads of the state-update and QK^T blocks
# speedup vs baseline: 1.0300x; 1.0205x over previous
.LBB0_740:
	v_mul_f32_e32 v0, 0x3fb8aa3b, v0
	v_exp_f32_e32 v0, v0
	v_cmp_eq_u32_e32 vcc, s28, v81
	s_and_saveexec_b64 s[90:91], vcc
	ds_write_b32 v89, v0
	s_or_b64 exec, exec, s[90:91]
	s_and_saveexec_b64 s[90:91], s[24:25]
	ds_write_b32 v91, v0
	s_or_b64 exec, exec, s[90:91]
	s_waitcnt lgkmcnt(0)
	s_barrier
	ds_read_b128 v[68:71], v73 offset:16384
	ds_read_b128 v[168:171], v73 offset:16400
	ds_read_b128 v[172:175], v115 offset:16384
	ds_read_b128 v[176:179], v115 offset:16400
	ds_read_b128 v[196:199], v161 offset:16384
	ds_read_b128 v[200:203], v161 offset:16400
	v_mul_f32_e32 v0, 0x3fb8aa3b, v64
	v_exp_f32_e32 v2, v0
	s_waitcnt lgkmcnt(3)
	v_sub_f32_e32 v0, v68, v172
	v_lshlrev_b32_e32 v204, 16, v56
	v_and_b32_e32 v205, 0xffff0000, v56
	v_sub_f32_e32 v56, v173, v69
	v_mul_f32_e32 v0, 0x3fb8aa3b, v0
	v_mul_f32_e32 v56, 0x3fb8aa3b, v56
	v_exp_f32_e32 v64, v0
	v_sub_f32_e32 v0, v172, v68
	v_mul_f32_e32 v3, 0x3fb8aa3b, v65
	v_sub_f32_e32 v65, v69, v173
	v_exp_f32_e32 v173, v56
	s_waitcnt lgkmcnt(1)
	v_sub_f32_e32 v56, v197, v69
	v_mul_f32_e32 v0, 0x3fb8aa3b, v0
	v_exp_f32_e32 v3, v3
	v_mul_f32_e32 v56, 0x3fb8aa3b, v56
	v_exp_f32_e32 v172, v0
	v_sub_f32_e32 v0, v196, v68
	v_exp_f32_e32 v56, v56
	v_mul_f32_e32 v0, 0x3fb8aa3b, v0
	v_exp_f32_e32 v0, v0
	v_pk_add_f32 v[2:3], v[2:3], 1.0 op_sel_hi:[1,0] neg_lo:[1,0] neg_hi:[1,0]
	v_mul_f32_e32 v65, 0x3fb8aa3b, v65
	v_pk_mul_f32 v[68:69], v[2:3], v[172:173]
	v_mul_f32_e32 v163, v3, v56
	v_sub_f32_e32 v3, v70, v174
	v_mul_f32_e32 v3, 0x3fb8aa3b, v3
	v_mul_f32_e32 v0, v2, v0
	v_mul_f32_e32 v2, 0x3fb8aa3b, v66
	v_exp_f32_e32 v66, v3
	v_sub_f32_e32 v3, v174, v70
	v_mul_f32_e32 v3, 0x3fb8aa3b, v3
	v_exp_f32_e32 v56, v3
	v_sub_f32_e32 v3, v198, v70
	v_mul_f32_e32 v3, 0x3fb8aa3b, v3
	v_exp_f32_e32 v70, v3
	v_mul_f32_e32 v3, 0x3fb8aa3b, v67
	v_sub_f32_e32 v67, v71, v175
	v_lshlrev_b32_e32 v172, 16, v57
	v_and_b32_e32 v173, 0xffff0000, v57
	v_sub_f32_e32 v57, v175, v71
	v_sub_f32_e32 v71, v199, v71
	v_exp_f32_e32 v2, v2
	v_exp_f32_e32 v3, v3
	v_mul_f32_e32 v57, 0x3fb8aa3b, v57
	v_mul_f32_e32 v71, 0x3fb8aa3b, v71
	v_exp_f32_e32 v57, v57
	v_exp_f32_e32 v166, v71
	v_pk_add_f32 v[2:3], v[2:3], 1.0 op_sel_hi:[1,0] neg_lo:[1,0] neg_hi:[1,0]
	v_mul_f32_e32 v67, 0x3fb8aa3b, v67
	v_mul_f32_e32 v174, v2, v70
	v_pk_mul_f32 v[70:71], v[2:3], v[56:57]
	v_mul_f32_e32 v166, v3, v166
	v_sub_f32_e32 v3, v168, v176
	v_sub_f32_e32 v57, v169, v177
	v_exp_f32_e32 v67, v67
	v_mul_f32_e32 v3, 0x3fb8aa3b, v3
	v_mul_f32_e32 v57, 0x3fb8aa3b, v57
	v_exp_f32_e32 v56, v3
	v_exp_f32_e32 v57, v57
	v_sub_f32_e32 v3, v176, v168
	v_pk_mul_f32 v[66:67], v[66:67], v[172:173]
	v_mul_f32_e32 v3, 0x3fb8aa3b, v3
	v_lshlrev_b32_e32 v172, 16, v58
	v_and_b32_e32 v173, 0xffff0000, v58
	v_mul_f32_e32 v2, 0x3fb8aa3b, v60
	v_exp_f32_e32 v60, v3
	s_waitcnt lgkmcnt(0)
	v_sub_f32_e32 v3, v200, v168
	v_pk_mul_f32 v[172:173], v[56:57], v[172:173]
	v_sub_f32_e32 v56, v177, v169
	v_mul_f32_e32 v3, 0x3fb8aa3b, v3
	v_mul_f32_e32 v56, 0x3fb8aa3b, v56
	v_exp_f32_e32 v168, v3
	v_mul_f32_e32 v3, 0x3fb8aa3b, v61
	v_exp_f32_e32 v61, v56
	v_sub_f32_e32 v56, v201, v169
	v_exp_f32_e32 v2, v2
	v_exp_f32_e32 v3, v3
	v_mul_f32_e32 v56, 0x3fb8aa3b, v56
	v_exp_f32_e32 v56, v56
	v_sub_f32_e32 v57, v171, v179
	v_pk_add_f32 v[2:3], v[2:3], 1.0 op_sel_hi:[1,0] neg_lo:[1,0] neg_hi:[1,0]
	v_mul_f32_e32 v57, 0x3fb8aa3b, v57
	v_pk_mul_f32 v[60:61], v[2:3], v[60:61]
	v_mul_f32_e32 v176, v3, v56
	v_sub_f32_e32 v3, v170, v178
	v_mul_f32_e32 v3, 0x3fb8aa3b, v3
	v_exp_f32_e32 v56, v3
	v_sub_f32_e32 v3, v178, v170
	v_mul_f32_e32 v3, 0x3fb8aa3b, v3
	v_exp_f32_e32 v57, v57
	v_exp_f32_e32 v58, v3
	v_sub_f32_e32 v3, v202, v170
	v_mul_f32_e32 v3, 0x3fb8aa3b, v3
	v_mul_f32_e32 v175, v2, v168
	v_mul_f32_e32 v2, 0x3fb8aa3b, v62
	v_exp_f32_e32 v168, v3
	v_mul_f32_e32 v3, 0x3fb8aa3b, v63
	v_lshlrev_b32_e32 v62, 16, v59
	v_and_b32_e32 v63, 0xffff0000, v59
	v_pk_mul_f32 v[62:63], v[56:57], v[62:63]
	v_sub_f32_e32 v56, v179, v171
	v_mul_f32_e32 v56, 0x3fb8aa3b, v56
	v_exp_f32_e32 v59, v56
	v_sub_f32_e32 v56, v203, v171
	v_exp_f32_e32 v65, v65
	v_exp_f32_e32 v2, v2
	v_exp_f32_e32 v3, v3
	v_mul_f32_e32 v56, 0x3fb8aa3b, v56
	v_exp_f32_e32 v56, v56
	v_pk_mul_f32 v[64:65], v[64:65], v[204:205]
	v_pk_add_f32 v[2:3], v[2:3], 1.0 op_sel_hi:[1,0] neg_lo:[1,0] neg_hi:[1,0]
	v_cvt_pk_bf16_f32 v57, v66, v67
	v_mul_f32_e32 v170, v2, v168
	v_pk_mul_f32 v[168:169], v[2:3], v[58:59]
	v_mul_f32_e32 v2, v3, v56
	v_cvt_pk_bf16_f32 v56, v64, v65
	v_cvt_pk_bf16_f32 v58, v172, v173
	v_cvt_pk_bf16_f32 v59, v62, v63
	ds_write_b128 v95, v[56:59] offset:32768
	v_cvt_pk_bf16_f32 v56, v68, v69
	v_cvt_pk_bf16_f32 v57, v70, v71
	v_cvt_pk_bf16_f32 v58, v60, v61
	v_cvt_pk_bf16_f32 v59, v168, v169
	v_cvt_pk_bf16_f32 v0, v0, s0
	ds_write_b128 v95, v[56:59] offset:41472
	ds_write_b16 v79, v0 offset:50176
	v_cvt_pk_bf16_f32 v0, v163, s0
	ds_write_b16 v79, v0 offset:50256
	v_cvt_pk_bf16_f32 v0, v174, s0
	ds_write_b16 v79, v0 offset:50336
	v_cvt_pk_bf16_f32 v0, v166, s0
	ds_write_b16 v79, v0 offset:50416
	v_cvt_pk_bf16_f32 v0, v175, s0
	ds_write_b16 v79, v0 offset:50496
	v_cvt_pk_bf16_f32 v0, v176, s0
	ds_write_b16 v79, v0 offset:50576
	v_cvt_pk_bf16_f32 v0, v170, s0
	ds_write_b16 v79, v0 offset:50656
	v_cvt_pk_bf16_f32 v0, v2, s0
	ds_write_b16 v79, v0 offset:50736
	ds_read_b128 v[206:209], v97
	ds_read_b128 v[210:213], v97 offset:64
	ds_read_b128 v[214:217], v97 offset:128
	ds_read_b128 v[218:221], v97 offset:192
	ds_read_b128 v[222:225], v97 offset:256
	ds_read_b128 v[226:229], v97 offset:320
	ds_read_b128 v[230:233], v97 offset:384
	ds_read_b128 v[234:237], v97 offset:448
	v_add_u32_e32 v0, v103, v99
	s_waitcnt lgkmcnt(7)
	v_pk_mul_f32 v[2:3], v[4:5], v[206:207]
	v_pk_mul_f32 v[56:57], v[6:7], v[208:209]
	v_cvt_pk_bf16_f32 v2, v2, v3
	v_cvt_pk_bf16_f32 v3, v56, v57
	ds_write_b64 v103, v[2:3]
	s_waitcnt lgkmcnt(7)
	v_pk_mul_f32 v[168:169], v[16:17], v[210:211]
	v_pk_mul_f32 v[170:171], v[18:19], v[212:213]
	v_cvt_pk_bf16_f32 v168, v168, v169
	v_cvt_pk_bf16_f32 v169, v170, v171
	ds_write_b64 v103, v[168:169] offset:32
	s_waitcnt lgkmcnt(7)
	v_pk_mul_f32 v[2:3], v[8:9], v[214:215]
	v_pk_mul_f32 v[56:57], v[10:11], v[216:217]
	v_cvt_pk_bf16_f32 v2, v2, v3
	v_cvt_pk_bf16_f32 v3, v56, v57
	ds_write_b64 v103, v[2:3] offset:64
	s_waitcnt lgkmcnt(7)
	v_pk_mul_f32 v[168:169], v[12:13], v[218:219]
	v_pk_mul_f32 v[170:171], v[14:15], v[220:221]
	v_cvt_pk_bf16_f32 v168, v168, v169
	v_cvt_pk_bf16_f32 v169, v170, v171
	ds_write_b64 v103, v[168:169] offset:96
	s_waitcnt lgkmcnt(7)
	v_pk_mul_f32 v[2:3], v[20:21], v[222:223]
	v_pk_mul_f32 v[56:57], v[22:23], v[224:225]
	v_cvt_pk_bf16_f32 v2, v2, v3
	v_cvt_pk_bf16_f32 v3, v56, v57
	ds_write_b64 v103, v[2:3] offset:128
	s_waitcnt lgkmcnt(7)
	v_pk_mul_f32 v[168:169], v[28:29], v[226:227]
	v_pk_mul_f32 v[170:171], v[30:31], v[228:229]
	v_cvt_pk_bf16_f32 v168, v168, v169
	v_cvt_pk_bf16_f32 v169, v170, v171
	ds_write_b64 v103, v[168:169] offset:160
	s_waitcnt lgkmcnt(7)
	v_pk_mul_f32 v[2:3], v[24:25], v[230:231]
	v_pk_mul_f32 v[56:57], v[26:27], v[232:233]
	v_cvt_pk_bf16_f32 v2, v2, v3
	v_cvt_pk_bf16_f32 v3, v56, v57
	ds_write_b64 v103, v[2:3] offset:192
	s_waitcnt lgkmcnt(7)
	v_pk_mul_f32 v[168:169], v[32:33], v[234:235]
	v_pk_mul_f32 v[170:171], v[34:35], v[236:237]
	v_cvt_pk_bf16_f32 v168, v168, v169
	v_cvt_pk_bf16_f32 v169, v170, v171
	ds_write_b64 v103, v[168:169] offset:224
	s_waitcnt lgkmcnt(0)
	s_barrier
	ds_read_b128 v[56:59], v129 offset:32768
	ds_read_b128 v[60:63], v0
	ds_read_b128 v[64:67], v0 offset:64
	ds_read_b128 v[68:71], v129 offset:32832
	s_waitcnt lgkmcnt(2)
	v_mfma_f32_16x16x32_bf16 v[56:59], v[56:59], v[60:63], 0
	ds_read_b128 v[168:171], v129 offset:37120
	ds_read_b128 v[172:175], v129 offset:37184
	s_waitcnt lgkmcnt(2)
	v_mfma_f32_16x16x32_bf16 v[56:59], v[68:71], v[64:67], v[56:59]
	ds_read_b128 v[68:71], v129 offset:32896
	s_waitcnt lgkmcnt(2)
	v_mfma_f32_16x16x32_bf16 v[60:63], v[168:171], v[60:63], 0
	s_waitcnt lgkmcnt(1)
	v_mfma_f32_16x16x32_bf16 v[60:63], v[172:175], v[64:67], v[60:63]
	ds_read_b128 v[64:67], v0 offset:128
	ds_read_b128 v[168:171], v0 offset:192
	ds_read_b128 v[172:175], v129 offset:32960
	s_waitcnt lgkmcnt(2)
	v_mfma_f32_16x16x32_bf16 v[56:59], v[68:71], v[64:67], v[56:59]
	ds_read_b128 v[68:71], v129 offset:37248
	ds_read_b128 v[176:179], v129 offset:37312
	s_waitcnt lgkmcnt(1)
	v_mfma_f32_16x16x32_bf16 v[60:63], v[68:71], v[64:67], v[60:63]
	v_mfma_f32_16x16x32_bf16 v[64:67], v[172:175], v[168:171], v[56:59]
	s_waitcnt lgkmcnt(0)
	v_mfma_f32_16x16x32_bf16 v[60:63], v[176:179], v[168:171], v[60:63]
	s_and_saveexec_b64 s[90:91], s[12:13]
	s_cbranch_execz .LBB0_746
	ds_read_b128 v[206:209], v107 offset:32768
	ds_read_b128 v[210:213], v113 offset:41472
	ds_read_b128 v[214:217], v107 offset:32832
	ds_read_b128 v[218:221], v113 offset:41536
	ds_read_b128 v[222:225], v107 offset:32896
	ds_read_b128 v[226:229], v113 offset:41600
	ds_read_b128 v[230:233], v107 offset:32960
	ds_read_b128 v[234:237], v113 offset:41664
	s_waitcnt lgkmcnt(6)
	v_mfma_f32_16x16x32_bf16 v[56:59], v[206:209], v[210:213], 0
	s_waitcnt lgkmcnt(4)
	v_mfma_f32_16x16x32_bf16 v[56:59], v[214:217], v[218:221], v[56:59]
	s_waitcnt lgkmcnt(2)
	v_mfma_f32_16x16x32_bf16 v[56:59], v[222:225], v[226:229], v[56:59]
	s_waitcnt lgkmcnt(0)
	v_mfma_f32_16x16x32_bf16 v[56:59], v[230:233], v[234:237], v[56:59]
	s_nop 7
	v_cvt_pk_bf16_f32 v0, v56, s0
	v_cndmask_b32_e64 v0, 0, v0, s[88:89]
	ds_write_b16 v130, v0
	v_cvt_pk_bf16_f32 v0, v57, s0
	v_cndmask_b32_e64 v0, 0, v0, s[86:87]
	ds_write_b16 v130, v0 offset:80
	v_cvt_pk_bf16_f32 v0, v58, s0
	v_cndmask_b32_e64 v0, 0, v0, s[84:85]
	ds_write_b16 v130, v0 offset:160
	v_cvt_pk_bf16_f32 v0, v59, s0
	v_cndmask_b32_e64 v0, 0, v0, s[82:83]
	ds_write_b16 v130, v0 offset:240

.LBB0_750:
	v_add_u32_e32 v0, 0x1ec00, v105
	s_nop 3
	ds_read_b128 v[206:209], v0
	ds_read_b128 v[210:213], v0 offset:64
	ds_read_b128 v[214:217], v0 offset:128
	ds_read_b128 v[218:221], v0 offset:192
	ds_read_b128 v[222:225], v0 offset:256
	ds_read_b128 v[226:229], v0 offset:320
	ds_read_b128 v[230:233], v0 offset:384
	ds_read_b128 v[234:237], v0 offset:448
	ds_read_b128 v[238:241], v120 offset:50176
	ds_read_b128 v[242:245], v119 offset:50176
	ds_read_b128 v[60:63], v118 offset:50176
	ds_read_b128 v[64:67], v123 offset:50176
	ds_read_b128 v[68:71], v124 offset:50176
	ds_read_b128 v[168:171], v125 offset:50176
	ds_read_b128 v[172:175], v126 offset:50176
	ds_read_b128 v[176:179], v127 offset:50176
	s_and_b64 vcc, exec, s[22:23]
	s_waitcnt lgkmcnt(7)
	v_pk_mul_f32 v[2:3], v[4:5], v[206:207]
	v_pk_mul_f32 v[4:5], v[6:7], v[208:209]
	v_pk_mul_f32 v[16:17], v[16:17], v[210:211]
	v_pk_mul_f32 v[18:19], v[18:19], v[212:213]
	v_pk_mul_f32 v[8:9], v[8:9], v[214:215]
	v_pk_mul_f32 v[10:11], v[10:11], v[216:217]
	v_pk_mul_f32 v[12:13], v[12:13], v[218:219]
	v_pk_mul_f32 v[14:15], v[14:15], v[220:221]
	v_pk_mul_f32 v[20:21], v[20:21], v[222:223]
	v_pk_mul_f32 v[22:23], v[22:23], v[224:225]
	v_pk_mul_f32 v[28:29], v[28:29], v[226:227]
	v_pk_mul_f32 v[30:31], v[30:31], v[228:229]
	v_pk_mul_f32 v[24:25], v[24:25], v[230:231]
	v_pk_mul_f32 v[26:27], v[26:27], v[232:233]
	v_pk_mul_f32 v[32:33], v[32:33], v[234:235]
	v_pk_mul_f32 v[34:35], v[34:35], v[236:237]
	v_mfma_f32_16x16x32_bf16 v[4:7], v[238:241], v[56:59], v[2:5]
	s_waitcnt lgkmcnt(6)
	v_mfma_f32_16x16x32_bf16 v[16:19], v[242:245], v[56:59], v[16:19]
	s_waitcnt lgkmcnt(5)
	v_mfma_f32_16x16x32_bf16 v[8:11], v[60:63], v[56:59], v[8:11]
	s_waitcnt lgkmcnt(4)
	v_mfma_f32_16x16x32_bf16 v[12:15], v[64:67], v[56:59], v[12:15]
	s_waitcnt lgkmcnt(3)
	v_mfma_f32_16x16x32_bf16 v[20:23], v[68:71], v[56:59], v[20:23]
	s_waitcnt lgkmcnt(2)
	v_mfma_f32_16x16x32_bf16 v[28:31], v[168:171], v[56:59], v[28:31]
	s_waitcnt lgkmcnt(1)
	v_mfma_f32_16x16x32_bf16 v[24:27], v[172:175], v[56:59], v[24:27]
	s_waitcnt lgkmcnt(0)
	s_barrier
	v_mfma_f32_16x16x32_bf16 v[32:35], v[176:179], v[56:59], v[32:35]
	s_cbranch_vccnz .LBB0_724
	ds_read_b128 v[64:67], v132
	ds_read_b128 v[56:59], v132 offset:16
	s_mov_b32 s28, 0x800000
	v_lshl_add_u32 v2, s92, 5, v135
	v_ashrrev_i32_e32 v3, 31, v2
	v_lshlrev_b64 v[2:3], 10, v[2:3]
	s_waitcnt lgkmcnt(0)
	v_pk_mul_f32 v[62:63], v[56:57], v[56:57]
	v_pk_mul_f32 v[60:61], v[58:59], v[58:59]
	v_pk_fma_f32 v[62:63], v[64:65], v[64:65], v[62:63]
	v_pk_fma_f32 v[60:61], v[66:67], v[66:67], v[60:61]
	v_add_f32_e32 v0, v62, v63
	v_add_f32_e32 v0, v60, v0
	v_add_f32_e32 v0, v61, v0
	v_and_b32_e32 v61, 64, v134
	v_xor_b32_e32 v60, 1, v134
	v_add_u32_e32 v61, 64, v61
	v_cmp_lt_i32_e32 vcc, v60, v61
	v_lshl_add_u64 v[2:3], v[108:109], 0, v[2:3]
	s_nop 0
	v_cndmask_b32_e32 v60, v134, v60, vcc
	v_lshlrev_b32_e32 v60, 2, v60
	ds_bpermute_b32 v60, v60, v0
	s_waitcnt lgkmcnt(0)
	v_add_f32_e32 v0, v0, v60
	v_xor_b32_e32 v60, 2, v134
	v_cmp_lt_i32_e32 vcc, v60, v61
	s_nop 1
	v_cndmask_b32_e32 v60, v134, v60, vcc
	v_lshlrev_b32_e32 v60, 2, v60
	ds_bpermute_b32 v60, v60, v0
	s_waitcnt lgkmcnt(0)
	v_add_f32_e32 v0, v0, v60
	v_xor_b32_e32 v60, 4, v134
	v_cmp_lt_i32_e32 vcc, v60, v61
	s_nop 1
	v_cndmask_b32_e32 v60, v134, v60, vcc
	v_lshlrev_b32_e32 v60, 2, v60
	ds_bpermute_b32 v60, v60, v0
	s_waitcnt lgkmcnt(0)
	v_add_f32_e32 v0, v0, v60
	v_xor_b32_e32 v60, 8, v134
	v_cmp_lt_i32_e32 vcc, v60, v61
	s_nop 1
	v_cndmask_b32_e32 v60, v134, v60, vcc
	v_lshlrev_b32_e32 v60, 2, v60
	ds_bpermute_b32 v60, v60, v0
	s_waitcnt lgkmcnt(0)
	v_add_f32_e32 v0, v0, v60
	v_fmamk_f32 v0, v0, 0x3c000000, v133
	v_cmp_gt_f32_e32 vcc, s28, v0
	v_mul_f32_e32 v60, 0x4b800000, v0
	s_nop 0
	v_cndmask_b32_e32 v0, v0, v60, vcc
	v_rsq_f32_e32 v0, v0
	s_nop 0
	v_mul_f32_e32 v60, 0x45800000, v0
	v_cndmask_b32_e32 v0, v0, v60, vcc
	global_load_dwordx4 v[60:63], v[110:111], off offset:16
	global_load_dwordx4 v[68:71], v[110:111], off
	v_pk_mul_f32 v[64:65], v[64:65], v[0:1] op_sel_hi:[1,0]
	v_pk_mul_f32 v[66:67], v[66:67], v[0:1] op_sel_hi:[1,0]
	s_waitcnt vmcnt(0)
	v_pk_mul_f32 v[64:65], v[68:69], v[64:65]
	v_lshlrev_b32_e32 v68, 16, v52
	v_and_b32_e32 v69, 0xffff0000, v52
	v_pk_mul_f32 v[66:67], v[70:71], v[66:67]
	v_lshlrev_b32_e32 v52, 16, v53
	v_and_b32_e32 v53, 0xffff0000, v53
	v_pk_mul_f32 v[66:67], v[66:67], v[52:53]
	v_pk_mul_f32 v[52:53], v[56:57], v[0:1] op_sel_hi:[1,0]
	v_lshlrev_b32_e32 v56, 16, v54
	v_pk_mul_f32 v[52:53], v[60:61], v[52:53]
	v_and_b32_e32 v57, 0xffff0000, v54
	v_pk_mul_f32 v[56:57], v[52:53], v[56:57]
	v_pk_mul_f32 v[52:53], v[58:59], v[0:1] op_sel_hi:[1,0]
	v_lshlrev_b32_e32 v54, 16, v55
	v_pk_mul_f32 v[52:53], v[62:63], v[52:53]
	v_and_b32_e32 v55, 0xffff0000, v55
	v_pk_mul_f32 v[64:65], v[64:65], v[68:69]
	v_pk_mul_f32 v[58:59], v[52:53], v[54:55]
	v_cvt_pk_bf16_f32 v52, v64, v65
	v_cvt_pk_bf16_f32 v53, v66, v67
	v_cvt_pk_bf16_f32 v54, v56, v57
	v_cvt_pk_bf16_f32 v55, v58, v59
	global_store_dwordx4 v[2:3], v[52:55], off
	s_branch .LBB0_724
